# A/B: per-phase s_setprio flips deleted from the three GEMM K-loops
# baseline (speedup 1.0000x reference)
; #define PG8_STAGE(bufoff, gbase, voff) do { _Pragma("unroll") for (int _i = 0; _i < 2; ++_i) \
;         __builtin_amdgcn_global_load_lds((const unsigned*)((const char*)(gbase) + (voff)[_i]), (PG8_LAS unsigned*)(lds + (bufoff) + ldsw + _i * 8192), 16, 0, 0); } while (0)
; #define PG8_LDA(dst, b, h) do { _Pragma("unroll") for (int m = 0; m < 4; ++m) _Pragma("unroll") for (int k = 0; k < 2; ++k) dst[m][k] = *(const PG8_LAS bf16x8*)(lds + PG8_SA(b, h) + aoff + m * 2048 + k * 1024); } while (0)
; #define PG8_LDB(dst, b, h) do { _Pragma("unroll") for (int n = 0; n < 2; ++n) _Pragma("unroll") for (int k = 0; k < 2; ++k) dst[n][k] = *(const PG8_LAS bf16x8*)(lds + PG8_SB(b, h) + boff + n * 2048 + k * 1024); } while (0)
; #define PG8_MMA(ai, bj, At, Bt) do { __builtin_amdgcn_s_setprio(1); _Pragma("unroll") for (int m = 0; m < 4; ++m) _Pragma("unroll") for (int n = 0; n < 2; ++n) _Pragma("unroll") for (int k = 0; k < 2; ++k) \
;         acc[ai][bj][m][n] = __builtin_amdgcn_mfma_f32_16x16x32_bf16(Bt[n][k], At[m][k], acc[ai][bj][m][n], 0, 0, 0); __builtin_amdgcn_s_setprio(0); } while (0)
; #define PG8_WAIT_V(n) asm volatile("s_waitcnt vmcnt(" #n ")" ::: "memory")
; #define PG8_WAIT_L(n) asm volatile("s_waitcnt lgkmcnt(" #n ")" ::: "memory")
; #define PG8_BAR __builtin_amdgcn_s_barrier()
; #define PG8_SCHED __builtin_amdgcn_sched_barrier(0)
; template <class Epi, class Sched, bool ALIGN_EPI = false, bool SP2 = false>
; __device__ __forceinline__ void gemm_phase(PG8_LAS unsigned char* lds, const Gemm g, const Sched& S, const Epi& E) {
;     ...
;             PG8_LDB(B0, 0, 0); PG8_LDB(B1, 0, 1); PG8_SCHED; PG8_LDA(At, 0, 0); PG8_STAGE(PG8_SA(1, 1), a1 + hstep, voffA);
;             PG8_WAIT_V(8); PG8_WAIT_L(0); PG8_BAR; PG8_MMA(0, 0, At, B0); PG8_MMA(0, 1, At, B1); PG8_BAR; PG8_SCHED;
;             PG8_LDA(At, 0, 1); PG8_STAGE(PG8_SB(0, 0), b2, voffB); PG8_STAGE(PG8_SB(0, 1), b2 + hstep, voffB); PG8_STAGE(PG8_SA(0, 0), a2, voffA);
;             PG8_WAIT_V(8); PG8_WAIT_L(0); PG8_BAR; PG8_MMA(1, 0, At, B0); PG8_MMA(1, 1, At, B1); PG8_BAR; PG8_SCHED;
.LBB0_231:
	ds_read_b128 v[46:49], v168
	ds_read_b128 v[50:53], v168 offset:1024
	ds_read_b128 v[54:57], v168 offset:2048
	ds_read_b128 v[58:61], v168 offset:3072
	ds_read_b128 v[162:165], v169
	ds_read_b128 v[174:177], v169 offset:1024
	ds_read_b128 v[180:183], v169 offset:2048
	ds_read_b128 v[184:187], v169 offset:3072
	s_add_u32 s70, s4, 0xfffc0080
	s_addc_u32 s71, s5, -1
	s_cmp_eq_u32 s69, 12
	s_cselect_b32 s85, s7, s71
	s_cselect_b32 s84, s8, s70
	s_cselect_b32 s71, s17, s68
	s_cselect_b32 s70, s65, s67
	v_lshl_add_u64 v[166:167], s[4:5], 0, v[158:159]
	s_add_i32 m0, s35, 0xc000
	ds_read_b128 v[188:191], v170
	ds_read_b128 v[192:195], v170 offset:1024
	ds_read_b128 v[196:199], v170 offset:2048
	ds_read_b128 v[200:203], v170 offset:3072
	ds_read_b128 v[204:207], v170 offset:4096
	ds_read_b128 v[208:211], v170 offset:5120
	ds_read_b128 v[212:215], v170 offset:6144
	ds_read_b128 v[216:219], v170 offset:7168
	global_load_lds_dwordx4 v[166:167], off
	v_lshl_add_u64 v[166:167], s[4:5], 0, v[160:161]
	s_add_i32 m0, s35, 0xe000
	s_nop 0
	global_load_lds_dwordx4 v[166:167], off
	s_waitcnt vmcnt(8)
	s_waitcnt lgkmcnt(0)
	s_barrier
	s_waitcnt lgkmcnt(0)
	v_mfma_f32_16x16x32_bf16 v[142:145], v[46:49], v[188:191], v[142:145]
	v_mfma_f32_16x16x32_bf16 v[138:141], v[54:57], v[188:191], v[138:141]
	v_mfma_f32_16x16x32_bf16 v[126:129], v[46:49], v[196:199], v[126:129]
	v_mfma_f32_16x16x32_bf16 v[122:125], v[54:57], v[196:199], v[122:125]
	v_mfma_f32_16x16x32_bf16 v[110:113], v[46:49], v[204:207], v[110:113]
	v_mfma_f32_16x16x32_bf16 v[106:109], v[54:57], v[204:207], v[106:109]
	v_mfma_f32_16x16x32_bf16 v[94:97], v[46:49], v[212:215], v[94:97]
	v_mfma_f32_16x16x32_bf16 v[90:93], v[54:57], v[212:215], v[90:93]
	v_mfma_f32_16x16x32_bf16 v[142:145], v[50:53], v[192:195], v[142:145]
	v_mfma_f32_16x16x32_bf16 v[138:141], v[58:61], v[192:195], v[138:141]
	v_mfma_f32_16x16x32_bf16 v[126:129], v[50:53], v[200:203], v[126:129]
	v_mfma_f32_16x16x32_bf16 v[122:125], v[58:61], v[200:203], v[122:125]
	v_mfma_f32_16x16x32_bf16 v[110:113], v[50:53], v[208:211], v[110:113]
	v_mfma_f32_16x16x32_bf16 v[106:109], v[58:61], v[208:211], v[106:109]
	v_mfma_f32_16x16x32_bf16 v[94:97], v[50:53], v[216:219], v[94:97]
	v_mfma_f32_16x16x32_bf16 v[90:93], v[58:61], v[216:219], v[90:93]
	v_mfma_f32_16x16x32_bf16 v[134:137], v[162:165], v[188:191], v[134:137]
	v_mfma_f32_16x16x32_bf16 v[130:133], v[180:183], v[188:191], v[130:133]
	v_mfma_f32_16x16x32_bf16 v[118:121], v[162:165], v[196:199], v[118:121]
	v_mfma_f32_16x16x32_bf16 v[114:117], v[180:183], v[196:199], v[114:117]
	v_mfma_f32_16x16x32_bf16 v[102:105], v[162:165], v[204:207], v[102:105]
	v_mfma_f32_16x16x32_bf16 v[98:101], v[180:183], v[204:207], v[98:101]
	v_mfma_f32_16x16x32_bf16 v[86:89], v[162:165], v[212:215], v[86:89]
	v_mfma_f32_16x16x32_bf16 v[82:85], v[180:183], v[212:215], v[82:85]
	v_mfma_f32_16x16x32_bf16 v[134:137], v[174:177], v[192:195], v[134:137]
	v_mfma_f32_16x16x32_bf16 v[130:133], v[184:187], v[192:195], v[130:133]
	v_mfma_f32_16x16x32_bf16 v[118:121], v[174:177], v[200:203], v[118:121]
	v_mfma_f32_16x16x32_bf16 v[114:117], v[184:187], v[200:203], v[114:117]
	v_mfma_f32_16x16x32_bf16 v[102:105], v[174:177], v[208:211], v[102:105]
	v_mfma_f32_16x16x32_bf16 v[98:101], v[184:187], v[208:211], v[98:101]
	v_mfma_f32_16x16x32_bf16 v[86:89], v[174:177], v[216:219], v[86:89]
	v_mfma_f32_16x16x32_bf16 v[82:85], v[184:187], v[216:219], v[82:85]
	s_barrier
	s_add_i32 s86, s58, s34
	v_lshl_add_u64 v[166:167], s[70:71], 0, v[148:149]
	s_mov_b32 m0, s86
	ds_read_b128 v[188:191], v170 offset:16384
	ds_read_b128 v[192:195], v170 offset:17408
	ds_read_b128 v[196:199], v170 offset:18432
	ds_read_b128 v[200:203], v170 offset:19456
	ds_read_b128 v[204:207], v170 offset:20480
	ds_read_b128 v[208:211], v170 offset:21504
	ds_read_b128 v[212:215], v170 offset:22528
	ds_read_b128 v[216:219], v170 offset:23552
	global_load_lds_dwordx4 v[166:167], off
	s_add_i32 m0, s86, 0x2000
	s_add_u32 s86, s70, 0x40000
	v_lshl_add_u64 v[220:221], s[70:71], 0, v[146:147]
	s_addc_u32 s87, s71, 0
	s_add_i32 s88, s59, s34
	global_load_lds_dwordx4 v[220:221], off
	v_lshl_add_u64 v[222:223], s[86:87], 0, v[148:149]
	s_mov_b32 m0, s88
	v_lshl_add_u64 v[224:225], s[84:85], 0, v[146:147]
	global_load_lds_dwordx4 v[222:223], off
	v_lshl_add_u64 v[222:223], s[86:87], 0, v[146:147]
	s_add_i32 m0, s88, 0x2000
	s_nop 0
	global_load_lds_dwordx4 v[222:223], off
	v_lshl_add_u64 v[222:223], s[84:85], 0, v[148:149]
	s_mov_b32 m0, s35
	s_nop 0
	global_load_lds_dwordx4 v[222:223], off
	s_mov_b32 m0, s72
	s_nop 0
	global_load_lds_dwordx4 v[224:225], off
	s_waitcnt vmcnt(8)
	s_waitcnt lgkmcnt(0)
	s_barrier
; #define PG8_STAGE(bufoff, gbase, voff) do { _Pragma("unroll") for (int _i = 0; _i < 2; ++_i) \
;         __builtin_amdgcn_global_load_lds((const unsigned*)((const char*)(gbase) + (voff)[_i]), (PG8_LAS unsigned*)(lds + (bufoff) + ldsw + _i * 8192), 16, 0, 0); } while (0)
; #define PG8_LDA(dst, b, h) do { _Pragma("unroll") for (int m = 0; m < 4; ++m) _Pragma("unroll") for (int k = 0; k < 2; ++k) dst[m][k] = *(const PG8_LAS bf16x8*)(lds + PG8_SA(b, h) + aoff + m * 2048 + k * 1024); } while (0)
; #define PG8_LDB(dst, b, h) do { _Pragma("unroll") for (int n = 0; n < 2; ++n) _Pragma("unroll") for (int k = 0; k < 2; ++k) dst[n][k] = *(const PG8_LAS bf16x8*)(lds + PG8_SB(b, h) + boff + n * 2048 + k * 1024); } while (0)
; #define PG8_MMA(ai, bj, At, Bt) do { __builtin_amdgcn_s_setprio(1); _Pragma("unroll") for (int m = 0; m < 4; ++m) _Pragma("unroll") for (int n = 0; n < 2; ++n) _Pragma("unroll") for (int k = 0; k < 2; ++k) \
;         acc[ai][bj][m][n] = __builtin_amdgcn_mfma_f32_16x16x32_bf16(Bt[n][k], At[m][k], acc[ai][bj][m][n], 0, 0, 0); __builtin_amdgcn_s_setprio(0); } while (0)
; #define PG8_WAIT_V(n) asm volatile("s_waitcnt vmcnt(" #n ")" ::: "memory")
; #define PG8_WAIT_L(n) asm volatile("s_waitcnt lgkmcnt(" #n ")" ::: "memory")
; #define PG8_BAR __builtin_amdgcn_s_barrier()
; #define PG8_SCHED __builtin_amdgcn_sched_barrier(0)
; template <class Epi, class Sched, bool ALIGN_EPI = false, bool SP2 = false>
; __device__ __forceinline__ void gemm_phase(PG8_LAS unsigned char* lds, const Gemm g, const Sched& S, const Epi& E) {
;     ...
;             PG8_WAIT_V(8); PG8_WAIT_L(0); PG8_BAR; PG8_MMA(1, 0, At, B0); PG8_MMA(1, 1, At, B1); PG8_BAR; PG8_SCHED;
;             PG8_LDB(B0, 1, 0); PG8_LDB(B1, 1, 1); PG8_SCHED; PG8_LDA(At, 1, 0); PG8_STAGE(PG8_SA(0, 1), a2 + hstep, voffA);
;             PG8_WAIT_V(8); PG8_WAIT_L(0); PG8_BAR; PG8_MMA(0, 0, At, B0); PG8_MMA(0, 1, At, B1); PG8_BAR; PG8_SCHED;
	s_waitcnt lgkmcnt(0)
	v_mfma_f32_16x16x32_bf16 v[78:81], v[46:49], v[188:191], v[78:81]
	v_mfma_f32_16x16x32_bf16 v[74:77], v[54:57], v[188:191], v[74:77]
	v_mfma_f32_16x16x32_bf16 v[62:65], v[46:49], v[196:199], v[62:65]
	v_mfma_f32_16x16x32_bf16 v[42:45], v[54:57], v[196:199], v[42:45]
	v_mfma_f32_16x16x32_bf16 v[30:33], v[46:49], v[204:207], v[30:33]
	v_mfma_f32_16x16x32_bf16 v[26:29], v[54:57], v[204:207], v[26:29]
	v_mfma_f32_16x16x32_bf16 v[14:17], v[46:49], v[212:215], v[14:17]
	v_mfma_f32_16x16x32_bf16 v[10:13], v[54:57], v[212:215], v[10:13]
	v_mfma_f32_16x16x32_bf16 v[78:81], v[50:53], v[192:195], v[78:81]
	v_mfma_f32_16x16x32_bf16 v[74:77], v[58:61], v[192:195], v[74:77]
	v_mfma_f32_16x16x32_bf16 v[62:65], v[50:53], v[200:203], v[62:65]
	v_mfma_f32_16x16x32_bf16 v[42:45], v[58:61], v[200:203], v[42:45]
	v_mfma_f32_16x16x32_bf16 v[30:33], v[50:53], v[208:211], v[30:33]
	v_mfma_f32_16x16x32_bf16 v[26:29], v[58:61], v[208:211], v[26:29]
	v_mfma_f32_16x16x32_bf16 v[14:17], v[50:53], v[216:219], v[14:17]
	v_mfma_f32_16x16x32_bf16 v[10:13], v[58:61], v[216:219], v[10:13]
	v_mfma_f32_16x16x32_bf16 v[38:41], v[162:165], v[196:199], v[38:41]
	v_mfma_f32_16x16x32_bf16 v[34:37], v[180:183], v[196:199], v[34:37]
	v_mfma_f32_16x16x32_bf16 v[22:25], v[162:165], v[204:207], v[22:25]
	v_mfma_f32_16x16x32_bf16 v[18:21], v[180:183], v[204:207], v[18:21]
	v_mfma_f32_16x16x32_bf16 v[6:9], v[162:165], v[212:215], v[6:9]
	v_mfma_f32_16x16x32_bf16 v[2:5], v[180:183], v[212:215], v[2:5]
	v_mfma_f32_16x16x32_bf16 v[46:49], v[162:165], v[188:191], v[70:73]
	v_mfma_f32_16x16x32_bf16 v[50:53], v[180:183], v[188:191], v[66:69]
	v_mfma_f32_16x16x32_bf16 v[38:41], v[174:177], v[200:203], v[38:41]
	v_mfma_f32_16x16x32_bf16 v[34:37], v[184:187], v[200:203], v[34:37]
	v_mfma_f32_16x16x32_bf16 v[22:25], v[174:177], v[208:211], v[22:25]
	v_mfma_f32_16x16x32_bf16 v[18:21], v[184:187], v[208:211], v[18:21]
	v_mfma_f32_16x16x32_bf16 v[6:9], v[174:177], v[216:219], v[6:9]
	v_mfma_f32_16x16x32_bf16 v[2:5], v[184:187], v[216:219], v[2:5]
	v_mfma_f32_16x16x32_bf16 v[46:49], v[174:177], v[192:195], v[46:49]
	v_mfma_f32_16x16x32_bf16 v[50:53], v[184:187], v[192:195], v[50:53]
	s_barrier
	s_add_i32 s86, 0, 0x18000
	s_add_i32 s87, 0, 0x1c000
	v_add_u32_e32 v70, s86, v153
	v_add_u32_e32 v150, s87, v153
	ds_read_b128 v[54:57], v70
	ds_read_b128 v[58:61], v70 offset:1024
	ds_read_b128 v[66:69], v70 offset:2048
	ds_read_b128 v[70:73], v70 offset:3072
	ds_read_b128 v[162:165], v150
	ds_read_b128 v[174:177], v150 offset:1024
	ds_read_b128 v[180:183], v150 offset:2048
	ds_read_b128 v[184:187], v150 offset:3072
	s_add_u32 s84, s84, 0x40000
	s_addc_u32 s85, s85, 0
	s_mov_b32 m0, s73
	v_lshl_add_u64 v[226:227], s[84:85], 0, v[148:149]
	ds_read_b128 v[188:191], v170 offset:32768
	ds_read_b128 v[192:195], v170 offset:33792
	ds_read_b128 v[196:199], v170 offset:34816
	ds_read_b128 v[200:203], v170 offset:35840
	ds_read_b128 v[204:207], v170 offset:36864
	ds_read_b128 v[208:211], v170 offset:37888
	ds_read_b128 v[212:215], v170 offset:38912
	ds_read_b128 v[216:219], v170 offset:39936
	global_load_lds_dwordx4 v[226:227], off
	v_lshl_add_u64 v[226:227], s[84:85], 0, v[146:147]
	s_mov_b32 m0, s79
	s_nop 0
	global_load_lds_dwordx4 v[226:227], off
	s_waitcnt vmcnt(8)
	s_waitcnt lgkmcnt(0)
	s_barrier
	s_waitcnt lgkmcnt(0)
	v_mfma_f32_16x16x32_bf16 v[142:145], v[54:57], v[188:191], v[142:145]
	v_mfma_f32_16x16x32_bf16 v[138:141], v[66:69], v[188:191], v[138:141]
	v_mfma_f32_16x16x32_bf16 v[126:129], v[54:57], v[196:199], v[126:129]
	v_mfma_f32_16x16x32_bf16 v[122:125], v[66:69], v[196:199], v[122:125]
	v_mfma_f32_16x16x32_bf16 v[110:113], v[54:57], v[204:207], v[110:113]
	v_mfma_f32_16x16x32_bf16 v[106:109], v[66:69], v[204:207], v[106:109]
	v_mfma_f32_16x16x32_bf16 v[94:97], v[54:57], v[212:215], v[94:97]
	v_mfma_f32_16x16x32_bf16 v[90:93], v[66:69], v[212:215], v[90:93]
	v_mfma_f32_16x16x32_bf16 v[142:145], v[58:61], v[192:195], v[142:145]
	v_mfma_f32_16x16x32_bf16 v[138:141], v[70:73], v[192:195], v[138:141]
	v_mfma_f32_16x16x32_bf16 v[126:129], v[58:61], v[200:203], v[126:129]
	v_mfma_f32_16x16x32_bf16 v[122:125], v[70:73], v[200:203], v[122:125]
	v_mfma_f32_16x16x32_bf16 v[110:113], v[58:61], v[208:211], v[110:113]
	v_mfma_f32_16x16x32_bf16 v[106:109], v[70:73], v[208:211], v[106:109]
	v_mfma_f32_16x16x32_bf16 v[94:97], v[58:61], v[216:219], v[94:97]
	v_mfma_f32_16x16x32_bf16 v[90:93], v[70:73], v[216:219], v[90:93]
	v_mfma_f32_16x16x32_bf16 v[134:137], v[162:165], v[188:191], v[134:137]
	v_mfma_f32_16x16x32_bf16 v[130:133], v[180:183], v[188:191], v[130:133]
	v_mfma_f32_16x16x32_bf16 v[118:121], v[162:165], v[196:199], v[118:121]
	v_mfma_f32_16x16x32_bf16 v[114:117], v[180:183], v[196:199], v[114:117]
	v_mfma_f32_16x16x32_bf16 v[102:105], v[162:165], v[204:207], v[102:105]
	v_mfma_f32_16x16x32_bf16 v[98:101], v[180:183], v[204:207], v[98:101]
	v_mfma_f32_16x16x32_bf16 v[86:89], v[162:165], v[212:215], v[86:89]
	v_mfma_f32_16x16x32_bf16 v[82:85], v[180:183], v[212:215], v[82:85]
	v_mfma_f32_16x16x32_bf16 v[134:137], v[174:177], v[192:195], v[134:137]
	v_mfma_f32_16x16x32_bf16 v[130:133], v[184:187], v[192:195], v[130:133]
	v_mfma_f32_16x16x32_bf16 v[118:121], v[174:177], v[200:203], v[118:121]
	v_mfma_f32_16x16x32_bf16 v[114:117], v[184:187], v[200:203], v[114:117]
	v_mfma_f32_16x16x32_bf16 v[102:105], v[174:177], v[208:211], v[102:105]
	v_mfma_f32_16x16x32_bf16 v[98:101], v[184:187], v[208:211], v[98:101]
	v_mfma_f32_16x16x32_bf16 v[86:89], v[174:177], v[216:219], v[86:89]
	v_mfma_f32_16x16x32_bf16 v[82:85], v[184:187], v[216:219], v[82:85]
	s_barrier
; #define PG8_WAIT_V(n) asm volatile("s_waitcnt vmcnt(" #n ")" ::: "memory")
; template <class Epi, class Sched, bool ALIGN_EPI = false, bool SP2 = false>
; __device__ __forceinline__ void gemm_phase(PG8_LAS unsigned char* lds, const Gemm g, const Sched& S, const Epi& E) {
;     ...
;         for (int t = 0; t < nt; t += 2) {
;     ...
;             PG8_LDA(At, 1, 1); PG8_STAGE(PG8_SB(1, 0), b3, voffB); PG8_STAGE(PG8_SB(1, 1), b3 + hstep, voffB); PG8_STAGE(PG8_SA(1, 0), a3, voffA);
;             PG8_WAIT_V(8); PG8_WAIT_L(0); PG8_BAR; PG8_MMA(1, 0, At, B0); PG8_MMA(1, 1, At, B1); PG8_BAR; PG8_SCHED;
;     __device__ __forceinline__ void operator()(const pg8::f32x4 (&acc)[2][2][4][2], const pg8::Unit& u, int wr, int wc, int fr, int fq) const {
;         const int b = u.pm / 9, w = u.pm % 9, pn = u.pn; const bool isctx = (w == 0);
;         const int grp = (pn == 0) ? 0 : (pn == 1) ? 1 : (pn < 4) ? 2 : (pn < 6) ? 3 : (pn < 8) ? 4 : (pn < 10) ? 5 : 6;
;         f32x4 gq[2][2];
;         if (grp == 4 || grp == 5) {
; #pragma unroll
;             for (int bj = 0; bj < 2; ++bj)
; #pragma unroll
;                 for (int n = 0; n < 2; ++n) gq[bj][n] = *(const f32x4*)(qkg + (grp == 5 ? 64 : 0) + 32 * bj + 16 * n + 4 * fq);
;         }
; #pragma unroll
;         for (int ai = 0; ai < 2; ++ai)
; #pragma unroll
;             for (int m = 0; m < 4; ++m) {
;                 const int rl = 128 * ai + 64 * wr + 16 * m + fr;
;                 const int tok = 256 * w + rl;
;                 const int l = tok - 256;
;                 f32x4 v[2][2];
; #pragma unroll
;                 for (int bj = 0; bj < 2; ++bj)
; #pragma unroll
;                     for (int n = 0; n < 2; ++n) v[bj][n] = acc[ai][bj][m][n];
;                 if (grp == 4 || grp == 5) {
;                     float ss = 0.f;
; #pragma unroll
;                     for (int bj = 0; bj < 2; ++bj)
; #pragma unroll
;                         for (int n = 0; n < 2; ++n) ss += (v[bj][n].x * v[bj][n].x + v[bj][n].y * v[bj][n].y) + (v[bj][n].z * v[bj][n].z + v[bj][n].w * v[bj][n].w);
;                     ss += __shfl_xor(ss, 16); ss += __shfl_xor(ss, 32);
;                     const float rstd = rsqrtf(ss * (1.f / 64.f) + EPS);
; #pragma unroll
;                     for (int bj = 0; bj < 2; ++bj)
; #pragma unroll
;                         for (int n = 0; n < 2; ++n) v[bj][n] = v[bj][n] * rstd * gq[bj][n];
;                 }
	s_add_i32 s84, s86, s34
	v_lshl_add_u64 v[166:167], v[166:167], 0, s[48:49]
	s_mov_b32 m0, s84
	ds_read_b128 v[188:191], v170 offset:49152
	ds_read_b128 v[192:195], v170 offset:50176
	ds_read_b128 v[196:199], v170 offset:51200
	ds_read_b128 v[200:203], v170 offset:52224
	ds_read_b128 v[204:207], v170 offset:53248
	ds_read_b128 v[208:211], v170 offset:54272
	ds_read_b128 v[212:215], v170 offset:55296
	ds_read_b128 v[216:219], v170 offset:56320
	global_load_lds_dwordx4 v[166:167], off
	s_add_i32 m0, s84, 0x2000
	s_add_u32 s70, s70, 0x40080
	v_lshl_add_u64 v[166:167], v[220:221], 0, s[48:49]
	s_addc_u32 s71, s71, 0
	s_add_i32 s84, s87, s34
	global_load_lds_dwordx4 v[166:167], off
	v_lshl_add_u64 v[166:167], s[70:71], 0, v[148:149]
	s_mov_b32 m0, s84
	s_nop 0
	global_load_lds_dwordx4 v[166:167], off
	v_lshl_add_u64 v[166:167], s[70:71], 0, v[146:147]
	s_add_i32 m0, s84, 0x2000
	s_nop 0
	global_load_lds_dwordx4 v[166:167], off
	v_lshl_add_u64 v[166:167], v[222:223], 0, s[48:49]
	s_mov_b32 m0, s74
	s_nop 0
	global_load_lds_dwordx4 v[166:167], off
	v_lshl_add_u64 v[166:167], v[224:225], 0, s[48:49]
	s_mov_b32 m0, s75
	s_nop 0
	global_load_lds_dwordx4 v[166:167], off
	s_waitcnt vmcnt(8)
	s_waitcnt lgkmcnt(0)
	s_barrier
	s_waitcnt lgkmcnt(0)
	v_mfma_f32_16x16x32_bf16 v[78:81], v[54:57], v[188:191], v[78:81]
	v_mfma_f32_16x16x32_bf16 v[74:77], v[66:69], v[188:191], v[74:77]
	v_mfma_f32_16x16x32_bf16 v[62:65], v[54:57], v[196:199], v[62:65]
	v_mfma_f32_16x16x32_bf16 v[42:45], v[66:69], v[196:199], v[42:45]
	v_mfma_f32_16x16x32_bf16 v[30:33], v[54:57], v[204:207], v[30:33]
	v_mfma_f32_16x16x32_bf16 v[26:29], v[66:69], v[204:207], v[26:29]
	v_mfma_f32_16x16x32_bf16 v[14:17], v[54:57], v[212:215], v[14:17]
	v_mfma_f32_16x16x32_bf16 v[10:13], v[66:69], v[212:215], v[10:13]
	v_mfma_f32_16x16x32_bf16 v[78:81], v[58:61], v[192:195], v[78:81]
	v_mfma_f32_16x16x32_bf16 v[74:77], v[70:73], v[192:195], v[74:77]
	v_mfma_f32_16x16x32_bf16 v[62:65], v[58:61], v[200:203], v[62:65]
	v_mfma_f32_16x16x32_bf16 v[42:45], v[70:73], v[200:203], v[42:45]
	v_mfma_f32_16x16x32_bf16 v[30:33], v[58:61], v[208:211], v[30:33]
	v_mfma_f32_16x16x32_bf16 v[26:29], v[70:73], v[208:211], v[26:29]
	v_mfma_f32_16x16x32_bf16 v[14:17], v[58:61], v[216:219], v[14:17]
	v_mfma_f32_16x16x32_bf16 v[10:13], v[70:73], v[216:219], v[10:13]
	v_mfma_f32_16x16x32_bf16 v[46:49], v[162:165], v[188:191], v[46:49]
	v_mfma_f32_16x16x32_bf16 v[70:73], v[174:177], v[192:195], v[46:49]
	v_mfma_f32_16x16x32_bf16 v[46:49], v[180:183], v[188:191], v[50:53]
	v_mfma_f32_16x16x32_bf16 v[38:41], v[162:165], v[196:199], v[38:41]
	v_mfma_f32_16x16x32_bf16 v[34:37], v[180:183], v[196:199], v[34:37]
	v_mfma_f32_16x16x32_bf16 v[22:25], v[162:165], v[204:207], v[22:25]
	v_mfma_f32_16x16x32_bf16 v[18:21], v[180:183], v[204:207], v[18:21]
	v_mfma_f32_16x16x32_bf16 v[6:9], v[162:165], v[212:215], v[6:9]
	v_mfma_f32_16x16x32_bf16 v[2:5], v[180:183], v[212:215], v[2:5]
	v_mfma_f32_16x16x32_bf16 v[66:69], v[184:187], v[192:195], v[46:49]
	v_mfma_f32_16x16x32_bf16 v[38:41], v[174:177], v[200:203], v[38:41]
	v_mfma_f32_16x16x32_bf16 v[34:37], v[184:187], v[200:203], v[34:37]
	v_mfma_f32_16x16x32_bf16 v[22:25], v[174:177], v[208:211], v[22:25]
	v_mfma_f32_16x16x32_bf16 v[18:21], v[184:187], v[208:211], v[18:21]
	v_mfma_f32_16x16x32_bf16 v[6:9], v[174:177], v[216:219], v[6:9]
	v_mfma_f32_16x16x32_bf16 v[2:5], v[184:187], v[216:219], v[2:5]
	s_barrier
	s_add_i32 s69, s69, 2
	s_add_u32 s4, s4, 0x100
	s_addc_u32 s5, s5, 0
	s_add_u32 s67, s67, 0x100
	s_addc_u32 s68, s68, 0
	s_cmp_gt_u32 s69, 13
	s_cbranch_scc0 .LBB0_231
	s_mul_hi_i32 s98, s6, 0x38e38e39
	s_lshr_b32 s99, s98, 31
	s_ashr_i32 s98, s98, 1
	s_add_i32 s98, s98, s99
	s_mul_i32 s98, s98, 9
	s_sub_i32 s98, s6, s98
	s_cmp_eq_u32 s98, 0
	s_cbranch_scc1 .Lp2_rope_pf_skip
	s_cmp_lt_u32 s16, 2
	s_cbranch_scc1 .Lp2_rope_pf_do
	s_cmp_lt_u32 s16, 6
	s_cbranch_scc1 .Lp2_rope_pf_skip
	s_cmp_gt_u32 s16, 9
	s_cbranch_scc1 .Lp2_rope_pf_skip

; #define PG8_STAGE(bufoff, gbase, voff) do { _Pragma("unroll") for (int _i = 0; _i < 2; ++_i) \
;         __builtin_amdgcn_global_load_lds((const unsigned*)((const char*)(gbase) + (voff)[_i]), (PG8_LAS unsigned*)(lds + (bufoff) + ldsw + _i * 8192), 16, 0, 0); } while (0)
; #define PG8_LDA(dst, b, h) do { _Pragma("unroll") for (int m = 0; m < 4; ++m) _Pragma("unroll") for (int k = 0; k < 2; ++k) dst[m][k] = *(const PG8_LAS bf16x8*)(lds + PG8_SA(b, h) + aoff + m * 2048 + k * 1024); } while (0)
; #define PG8_LDB(dst, b, h) do { _Pragma("unroll") for (int n = 0; n < 2; ++n) _Pragma("unroll") for (int k = 0; k < 2; ++k) dst[n][k] = *(const PG8_LAS bf16x8*)(lds + PG8_SB(b, h) + boff + n * 2048 + k * 1024); } while (0)
; #define PG8_MMA(ai, bj, At, Bt) do { __builtin_amdgcn_s_setprio(1); _Pragma("unroll") for (int m = 0; m < 4; ++m) _Pragma("unroll") for (int n = 0; n < 2; ++n) _Pragma("unroll") for (int k = 0; k < 2; ++k) \
;         acc[ai][bj][m][n] = __builtin_amdgcn_mfma_f32_16x16x32_bf16(Bt[n][k], At[m][k], acc[ai][bj][m][n], 0, 0, 0); __builtin_amdgcn_s_setprio(0); } while (0)
; #define PG8_WAIT_V(n) asm volatile("s_waitcnt vmcnt(" #n ")" ::: "memory")
; #define PG8_WAIT_L(n) asm volatile("s_waitcnt lgkmcnt(" #n ")" ::: "memory")
; #define PG8_BAR __builtin_amdgcn_s_barrier()
; #define PG8_SCHED __builtin_amdgcn_sched_barrier(0)
; template <class Epi, class Sched, bool ALIGN_EPI = false, bool SP2 = false>
; __device__ __forceinline__ void gemm_phase(PG8_LAS unsigned char* lds, const Gemm g, const Sched& S, const Epi& E) {
;     ...
;             PG8_LDB(B0, 0, 0); PG8_LDB(B1, 0, 1); PG8_SCHED; PG8_LDA(At, 0, 0); PG8_STAGE(PG8_SA(1, 1), a1 + hstep, voffA);
;             PG8_WAIT_V(8); PG8_WAIT_L(0); PG8_BAR; PG8_MMA(0, 0, At, B0); PG8_MMA(0, 1, At, B1); PG8_BAR; PG8_SCHED;
;             PG8_LDA(At, 0, 1); PG8_STAGE(PG8_SB(0, 0), b2, voffB); PG8_STAGE(PG8_SB(0, 1), b2 + hstep, voffB); PG8_STAGE(PG8_SA(0, 0), a2, voffA);
;             PG8_WAIT_V(8); PG8_WAIT_L(0); PG8_BAR; PG8_MMA(1, 0, At, B0); PG8_MMA(1, 1, At, B1); PG8_BAR; PG8_SCHED;
.LBB0_713:
	ds_read_b128 v[58:61], v209
	ds_read_b128 v[62:65], v209 offset:1024
	ds_read_b128 v[66:69], v209 offset:2048
	ds_read_b128 v[70:73], v209 offset:3072
	ds_read_b128 v[74:77], v210
	ds_read_b128 v[78:81], v210 offset:1024
	ds_read_b128 v[82:85], v210 offset:2048
	ds_read_b128 v[86:89], v210 offset:3072
	s_add_u32 s64, s62, 0xfffc0080
	s_addc_u32 s65, s63, -1
	s_cmp_eq_u32 s81, 12
	s_cselect_b32 s67, s10, s65
	s_cselect_b32 s66, s55, s64
	s_cselect_b32 s65, s53, s80
	s_cselect_b32 s64, s61, s79
	v_lshl_add_u64 v[222:223], s[62:63], 0, v[192:193]
	s_add_i32 m0, s9, 0xc000
	ds_read_b128 v[162:165], v211
	ds_read_b128 v[166:169], v211 offset:1024
	ds_read_b128 v[170:173], v211 offset:2048
	ds_read_b128 v[174:177], v211 offset:3072
	ds_read_b128 v[200:203], v211 offset:4096
	ds_read_b128 v[204:207], v211 offset:5120
	ds_read_b128 v[214:217], v211 offset:6144
	ds_read_b128 v[218:221], v211 offset:7168
	global_load_lds_dwordx4 v[222:223], off
	v_lshl_add_u64 v[222:223], s[62:63], 0, v[194:195]
	s_add_i32 m0, s9, 0xe000
	s_nop 0
	global_load_lds_dwordx4 v[222:223], off
	s_waitcnt vmcnt(8)
	s_waitcnt lgkmcnt(0)
	s_barrier
	s_waitcnt lgkmcnt(0)
	v_mfma_f32_16x16x32_bf16 v[158:161], v[58:61], v[162:165], v[158:161]
	v_mfma_f32_16x16x32_bf16 v[154:157], v[66:69], v[162:165], v[154:157]
	v_mfma_f32_16x16x32_bf16 v[142:145], v[58:61], v[170:173], v[142:145]
	v_mfma_f32_16x16x32_bf16 v[138:141], v[66:69], v[170:173], v[138:141]
	v_mfma_f32_16x16x32_bf16 v[126:129], v[58:61], v[200:203], v[126:129]
	v_mfma_f32_16x16x32_bf16 v[122:125], v[66:69], v[200:203], v[122:125]
	v_mfma_f32_16x16x32_bf16 v[110:113], v[58:61], v[214:217], v[110:113]
	v_mfma_f32_16x16x32_bf16 v[106:109], v[66:69], v[214:217], v[106:109]
	v_mfma_f32_16x16x32_bf16 v[158:161], v[62:65], v[166:169], v[158:161]
	v_mfma_f32_16x16x32_bf16 v[154:157], v[70:73], v[166:169], v[154:157]
	v_mfma_f32_16x16x32_bf16 v[142:145], v[62:65], v[174:177], v[142:145]
	v_mfma_f32_16x16x32_bf16 v[138:141], v[70:73], v[174:177], v[138:141]
	v_mfma_f32_16x16x32_bf16 v[126:129], v[62:65], v[204:207], v[126:129]
	v_mfma_f32_16x16x32_bf16 v[122:125], v[70:73], v[204:207], v[122:125]
	v_mfma_f32_16x16x32_bf16 v[110:113], v[62:65], v[218:221], v[110:113]
	v_mfma_f32_16x16x32_bf16 v[106:109], v[70:73], v[218:221], v[106:109]
	v_mfma_f32_16x16x32_bf16 v[150:153], v[74:77], v[162:165], v[150:153]
	v_mfma_f32_16x16x32_bf16 v[146:149], v[82:85], v[162:165], v[146:149]
	v_mfma_f32_16x16x32_bf16 v[134:137], v[74:77], v[170:173], v[134:137]
	v_mfma_f32_16x16x32_bf16 v[130:133], v[82:85], v[170:173], v[130:133]
	v_mfma_f32_16x16x32_bf16 v[118:121], v[74:77], v[200:203], v[118:121]
	v_mfma_f32_16x16x32_bf16 v[114:117], v[82:85], v[200:203], v[114:117]
	v_mfma_f32_16x16x32_bf16 v[102:105], v[74:77], v[214:217], v[102:105]
	v_mfma_f32_16x16x32_bf16 v[98:101], v[82:85], v[214:217], v[98:101]
	v_mfma_f32_16x16x32_bf16 v[150:153], v[78:81], v[166:169], v[150:153]
	v_mfma_f32_16x16x32_bf16 v[146:149], v[86:89], v[166:169], v[146:149]
	v_mfma_f32_16x16x32_bf16 v[134:137], v[78:81], v[174:177], v[134:137]
	v_mfma_f32_16x16x32_bf16 v[130:133], v[86:89], v[174:177], v[130:133]
	v_mfma_f32_16x16x32_bf16 v[118:121], v[78:81], v[204:207], v[118:121]
	v_mfma_f32_16x16x32_bf16 v[114:117], v[86:89], v[204:207], v[114:117]
	v_mfma_f32_16x16x32_bf16 v[102:105], v[78:81], v[218:221], v[102:105]
	v_mfma_f32_16x16x32_bf16 v[98:101], v[86:89], v[218:221], v[98:101]
	s_barrier
	s_add_i32 s82, s74, s33
	v_lshl_add_u64 v[222:223], s[64:65], 0, v[180:181]
	s_mov_b32 m0, s82
	ds_read_b128 v[162:165], v211 offset:16384
	ds_read_b128 v[166:169], v211 offset:17408
	ds_read_b128 v[170:173], v211 offset:18432
	ds_read_b128 v[174:177], v211 offset:19456
	ds_read_b128 v[200:203], v211 offset:20480
	ds_read_b128 v[204:207], v211 offset:21504
	ds_read_b128 v[214:217], v211 offset:22528
	ds_read_b128 v[218:221], v211 offset:23552
	global_load_lds_dwordx4 v[222:223], off
	s_add_i32 m0, s82, 0x2000
	s_add_u32 s82, s64, 0x40000
	v_lshl_add_u64 v[224:225], s[64:65], 0, v[182:183]
	s_addc_u32 s83, s65, 0
	s_add_i32 s84, s75, s33
	global_load_lds_dwordx4 v[224:225], off
	v_lshl_add_u64 v[226:227], s[82:83], 0, v[180:181]
	s_mov_b32 m0, s84
	v_lshl_add_u64 v[228:229], s[66:67], 0, v[182:183]
	global_load_lds_dwordx4 v[226:227], off
	v_lshl_add_u64 v[226:227], s[82:83], 0, v[182:183]
	s_add_i32 m0, s84, 0x2000
	s_nop 0
	global_load_lds_dwordx4 v[226:227], off
	v_lshl_add_u64 v[226:227], s[66:67], 0, v[180:181]
	s_mov_b32 m0, s9
	s_nop 0
	global_load_lds_dwordx4 v[226:227], off
	s_mov_b32 m0, s34
	s_nop 0
	global_load_lds_dwordx4 v[228:229], off
	s_waitcnt vmcnt(8)
	s_waitcnt lgkmcnt(0)
	s_barrier
; #define PG8_STAGE(bufoff, gbase, voff) do { _Pragma("unroll") for (int _i = 0; _i < 2; ++_i) \
;         __builtin_amdgcn_global_load_lds((const unsigned*)((const char*)(gbase) + (voff)[_i]), (PG8_LAS unsigned*)(lds + (bufoff) + ldsw + _i * 8192), 16, 0, 0); } while (0)
; #define PG8_LDA(dst, b, h) do { _Pragma("unroll") for (int m = 0; m < 4; ++m) _Pragma("unroll") for (int k = 0; k < 2; ++k) dst[m][k] = *(const PG8_LAS bf16x8*)(lds + PG8_SA(b, h) + aoff + m * 2048 + k * 1024); } while (0)
; #define PG8_LDB(dst, b, h) do { _Pragma("unroll") for (int n = 0; n < 2; ++n) _Pragma("unroll") for (int k = 0; k < 2; ++k) dst[n][k] = *(const PG8_LAS bf16x8*)(lds + PG8_SB(b, h) + boff + n * 2048 + k * 1024); } while (0)
; #define PG8_MMA(ai, bj, At, Bt) do { __builtin_amdgcn_s_setprio(1); _Pragma("unroll") for (int m = 0; m < 4; ++m) _Pragma("unroll") for (int n = 0; n < 2; ++n) _Pragma("unroll") for (int k = 0; k < 2; ++k) \
;         acc[ai][bj][m][n] = __builtin_amdgcn_mfma_f32_16x16x32_bf16(Bt[n][k], At[m][k], acc[ai][bj][m][n], 0, 0, 0); __builtin_amdgcn_s_setprio(0); } while (0)
; #define PG8_WAIT_V(n) asm volatile("s_waitcnt vmcnt(" #n ")" ::: "memory")
; template <class Epi, class Sched, bool ALIGN_EPI = false, bool SP2 = false>
; __device__ __forceinline__ void gemm_phase(PG8_LAS unsigned char* lds, const Gemm g, const Sched& S, const Epi& E) {
;     ...
;             PG8_LDB(B0, 0, 0); PG8_LDB(B1, 0, 1); PG8_SCHED; PG8_LDA(At, 0, 0); PG8_STAGE(PG8_SA(1, 1), a1 + hstep, voffA);
;             PG8_WAIT_V(8); PG8_WAIT_L(0); PG8_BAR; PG8_MMA(0, 0, At, B0); PG8_MMA(0, 1, At, B1); PG8_BAR; PG8_SCHED;
;             PG8_LDA(At, 0, 1); PG8_STAGE(PG8_SB(0, 0), b2, voffB); PG8_STAGE(PG8_SB(0, 1), b2 + hstep, voffB); PG8_STAGE(PG8_SA(0, 0), a2, voffA);
;             PG8_WAIT_V(8); PG8_WAIT_L(0); PG8_BAR; PG8_MMA(1, 0, At, B0); PG8_MMA(1, 1, At, B1); PG8_BAR; PG8_SCHED;
;             PG8_LDB(B0, 1, 0); PG8_LDB(B1, 1, 1); PG8_SCHED; PG8_LDA(At, 1, 0); PG8_STAGE(PG8_SA(0, 1), a2 + hstep, voffA);
;             PG8_WAIT_V(8); PG8_WAIT_L(0); PG8_BAR; PG8_MMA(0, 0, At, B0); PG8_MMA(0, 1, At, B1); PG8_BAR; PG8_SCHED;
;             PG8_LDA(At, 1, 1); PG8_STAGE(PG8_SB(1, 0), b3, voffB); PG8_STAGE(PG8_SB(1, 1), b3 + hstep, voffB); PG8_STAGE(PG8_SA(1, 0), a3, voffA);
;             PG8_WAIT_V(8); PG8_WAIT_L(0); PG8_BAR; PG8_MMA(1, 0, At, B0); PG8_MMA(1, 1, At, B1); PG8_BAR; PG8_SCHED;
	s_waitcnt lgkmcnt(0)
	v_mfma_f32_16x16x32_bf16 v[94:97], v[58:61], v[162:165], v[94:97]
	v_mfma_f32_16x16x32_bf16 v[90:93], v[66:69], v[162:165], v[90:93]
	v_mfma_f32_16x16x32_bf16 v[46:49], v[58:61], v[170:173], v[46:49]
	v_mfma_f32_16x16x32_bf16 v[42:45], v[66:69], v[170:173], v[42:45]
	v_mfma_f32_16x16x32_bf16 v[30:33], v[58:61], v[200:203], v[30:33]
	v_mfma_f32_16x16x32_bf16 v[26:29], v[66:69], v[200:203], v[26:29]
	v_mfma_f32_16x16x32_bf16 v[14:17], v[58:61], v[214:217], v[14:17]
	v_mfma_f32_16x16x32_bf16 v[10:13], v[66:69], v[214:217], v[10:13]
	v_mfma_f32_16x16x32_bf16 v[94:97], v[62:65], v[166:169], v[94:97]
	v_mfma_f32_16x16x32_bf16 v[90:93], v[70:73], v[166:169], v[90:93]
	v_mfma_f32_16x16x32_bf16 v[46:49], v[62:65], v[174:177], v[46:49]
	v_mfma_f32_16x16x32_bf16 v[42:45], v[70:73], v[174:177], v[42:45]
	v_mfma_f32_16x16x32_bf16 v[30:33], v[62:65], v[204:207], v[30:33]
	v_mfma_f32_16x16x32_bf16 v[26:29], v[70:73], v[204:207], v[26:29]
	v_mfma_f32_16x16x32_bf16 v[14:17], v[62:65], v[218:221], v[14:17]
	v_mfma_f32_16x16x32_bf16 v[10:13], v[70:73], v[218:221], v[10:13]
	v_mfma_f32_16x16x32_bf16 v[54:57], v[74:77], v[162:165], v[54:57]
	v_mfma_f32_16x16x32_bf16 v[50:53], v[82:85], v[162:165], v[50:53]
	v_mfma_f32_16x16x32_bf16 v[38:41], v[74:77], v[170:173], v[38:41]
	v_mfma_f32_16x16x32_bf16 v[34:37], v[82:85], v[170:173], v[34:37]
	v_mfma_f32_16x16x32_bf16 v[22:25], v[74:77], v[200:203], v[22:25]
	v_mfma_f32_16x16x32_bf16 v[18:21], v[82:85], v[200:203], v[18:21]
	v_mfma_f32_16x16x32_bf16 v[6:9], v[74:77], v[214:217], v[6:9]
	v_mfma_f32_16x16x32_bf16 v[2:5], v[82:85], v[214:217], v[2:5]
	v_mfma_f32_16x16x32_bf16 v[54:57], v[78:81], v[166:169], v[54:57]
	v_mfma_f32_16x16x32_bf16 v[50:53], v[86:89], v[166:169], v[50:53]
	v_mfma_f32_16x16x32_bf16 v[38:41], v[78:81], v[174:177], v[38:41]
	v_mfma_f32_16x16x32_bf16 v[34:37], v[86:89], v[174:177], v[34:37]
	v_mfma_f32_16x16x32_bf16 v[22:25], v[78:81], v[204:207], v[22:25]
	v_mfma_f32_16x16x32_bf16 v[18:21], v[86:89], v[204:207], v[18:21]
	v_mfma_f32_16x16x32_bf16 v[6:9], v[78:81], v[218:221], v[6:9]
	v_mfma_f32_16x16x32_bf16 v[2:5], v[86:89], v[218:221], v[2:5]
	s_barrier
	s_add_i32 s82, 0, 0x18000
	s_add_i32 s83, 0, 0x1c000
	v_add_u32_e32 v70, s82, v179
	v_add_u32_e32 v86, s83, v179
	ds_read_b128 v[58:61], v70
	ds_read_b128 v[62:65], v70 offset:1024
	ds_read_b128 v[66:69], v70 offset:2048
	ds_read_b128 v[70:73], v70 offset:3072
	ds_read_b128 v[74:77], v86
	ds_read_b128 v[78:81], v86 offset:1024
	ds_read_b128 v[82:85], v86 offset:2048
	ds_read_b128 v[86:89], v86 offset:3072
	s_add_u32 s66, s66, 0x40000
	s_addc_u32 s67, s67, 0
	s_mov_b32 m0, s35
	v_lshl_add_u64 v[230:231], s[66:67], 0, v[180:181]
	ds_read_b128 v[162:165], v211 offset:32768
	ds_read_b128 v[166:169], v211 offset:33792
	ds_read_b128 v[170:173], v211 offset:34816
	ds_read_b128 v[174:177], v211 offset:35840
	ds_read_b128 v[200:203], v211 offset:36864
	ds_read_b128 v[204:207], v211 offset:37888
	ds_read_b128 v[214:217], v211 offset:38912
	ds_read_b128 v[218:221], v211 offset:39936
	global_load_lds_dwordx4 v[230:231], off
	v_lshl_add_u64 v[230:231], s[66:67], 0, v[182:183]
	s_mov_b32 m0, s42
	s_nop 0
	global_load_lds_dwordx4 v[230:231], off
	s_waitcnt vmcnt(8)
	s_waitcnt lgkmcnt(0)
	s_barrier
	s_waitcnt lgkmcnt(0)
	v_mfma_f32_16x16x32_bf16 v[158:161], v[58:61], v[162:165], v[158:161]
	v_mfma_f32_16x16x32_bf16 v[154:157], v[66:69], v[162:165], v[154:157]
	v_mfma_f32_16x16x32_bf16 v[142:145], v[58:61], v[170:173], v[142:145]
	v_mfma_f32_16x16x32_bf16 v[138:141], v[66:69], v[170:173], v[138:141]
	v_mfma_f32_16x16x32_bf16 v[126:129], v[58:61], v[200:203], v[126:129]
	v_mfma_f32_16x16x32_bf16 v[122:125], v[66:69], v[200:203], v[122:125]
	v_mfma_f32_16x16x32_bf16 v[110:113], v[58:61], v[214:217], v[110:113]
	v_mfma_f32_16x16x32_bf16 v[106:109], v[66:69], v[214:217], v[106:109]
	v_mfma_f32_16x16x32_bf16 v[158:161], v[62:65], v[166:169], v[158:161]
	v_mfma_f32_16x16x32_bf16 v[154:157], v[70:73], v[166:169], v[154:157]
	v_mfma_f32_16x16x32_bf16 v[142:145], v[62:65], v[174:177], v[142:145]
	v_mfma_f32_16x16x32_bf16 v[138:141], v[70:73], v[174:177], v[138:141]
	v_mfma_f32_16x16x32_bf16 v[126:129], v[62:65], v[204:207], v[126:129]
	v_mfma_f32_16x16x32_bf16 v[122:125], v[70:73], v[204:207], v[122:125]
	v_mfma_f32_16x16x32_bf16 v[110:113], v[62:65], v[218:221], v[110:113]
	v_mfma_f32_16x16x32_bf16 v[106:109], v[70:73], v[218:221], v[106:109]
	v_mfma_f32_16x16x32_bf16 v[150:153], v[74:77], v[162:165], v[150:153]
	v_mfma_f32_16x16x32_bf16 v[146:149], v[82:85], v[162:165], v[146:149]
	v_mfma_f32_16x16x32_bf16 v[134:137], v[74:77], v[170:173], v[134:137]
	v_mfma_f32_16x16x32_bf16 v[130:133], v[82:85], v[170:173], v[130:133]
	v_mfma_f32_16x16x32_bf16 v[118:121], v[74:77], v[200:203], v[118:121]
	v_mfma_f32_16x16x32_bf16 v[114:117], v[82:85], v[200:203], v[114:117]
	v_mfma_f32_16x16x32_bf16 v[102:105], v[74:77], v[214:217], v[102:105]
	v_mfma_f32_16x16x32_bf16 v[98:101], v[82:85], v[214:217], v[98:101]
	v_mfma_f32_16x16x32_bf16 v[150:153], v[78:81], v[166:169], v[150:153]
	v_mfma_f32_16x16x32_bf16 v[146:149], v[86:89], v[166:169], v[146:149]
	v_mfma_f32_16x16x32_bf16 v[134:137], v[78:81], v[174:177], v[134:137]
	v_mfma_f32_16x16x32_bf16 v[130:133], v[86:89], v[174:177], v[130:133]
	v_mfma_f32_16x16x32_bf16 v[118:121], v[78:81], v[204:207], v[118:121]
	v_mfma_f32_16x16x32_bf16 v[114:117], v[86:89], v[204:207], v[114:117]
	v_mfma_f32_16x16x32_bf16 v[102:105], v[78:81], v[218:221], v[102:105]
	v_mfma_f32_16x16x32_bf16 v[98:101], v[86:89], v[218:221], v[98:101]
	s_barrier
; #define PG8_STAGE(bufoff, gbase, voff) do { _Pragma("unroll") for (int _i = 0; _i < 2; ++_i) \
;         __builtin_amdgcn_global_load_lds((const unsigned*)((const char*)(gbase) + (voff)[_i]), (PG8_LAS unsigned*)(lds + (bufoff) + ldsw + _i * 8192), 16, 0, 0); } while (0)
; #define PG8_LDA(dst, b, h) do { _Pragma("unroll") for (int m = 0; m < 4; ++m) _Pragma("unroll") for (int k = 0; k < 2; ++k) dst[m][k] = *(const PG8_LAS bf16x8*)(lds + PG8_SA(b, h) + aoff + m * 2048 + k * 1024); } while (0)
; #define PG8_MMA(ai, bj, At, Bt) do { __builtin_amdgcn_s_setprio(1); _Pragma("unroll") for (int m = 0; m < 4; ++m) _Pragma("unroll") for (int n = 0; n < 2; ++n) _Pragma("unroll") for (int k = 0; k < 2; ++k) \
;         acc[ai][bj][m][n] = __builtin_amdgcn_mfma_f32_16x16x32_bf16(Bt[n][k], At[m][k], acc[ai][bj][m][n], 0, 0, 0); __builtin_amdgcn_s_setprio(0); } while (0)
; #define PG8_WAIT_V(n) asm volatile("s_waitcnt vmcnt(" #n ")" ::: "memory")
; #define PG8_WAIT_L(n) asm volatile("s_waitcnt lgkmcnt(" #n ")" ::: "memory")
; #define PG8_BAR __builtin_amdgcn_s_barrier()
; #define PG8_SCHED __builtin_amdgcn_sched_barrier(0)
; template <class Epi, class Sched, bool ALIGN_EPI = false, bool SP2 = false>
; __device__ __forceinline__ void gemm_phase(PG8_LAS unsigned char* lds, const Gemm g, const Sched& S, const Epi& E) {
;     ...
;         for (int t = 0; t < nt; t += 2) {
;             const bool last = (t == nt - 2);
;     ...
;             PG8_LDA(At, 1, 1); PG8_STAGE(PG8_SB(1, 0), b3, voffB); PG8_STAGE(PG8_SB(1, 1), b3 + hstep, voffB); PG8_STAGE(PG8_SA(1, 0), a3, voffA);
;             PG8_WAIT_V(8); PG8_WAIT_L(0); PG8_BAR; PG8_MMA(1, 0, At, B0); PG8_MMA(1, 1, At, B1); PG8_BAR; PG8_SCHED;
	s_add_i32 s66, s82, s33
	v_lshl_add_u64 v[222:223], v[222:223], 0, s[22:23]
	s_mov_b32 m0, s66
	ds_read_b128 v[162:165], v211 offset:49152
	ds_read_b128 v[166:169], v211 offset:50176
	ds_read_b128 v[170:173], v211 offset:51200
	ds_read_b128 v[174:177], v211 offset:52224
	ds_read_b128 v[200:203], v211 offset:53248
	ds_read_b128 v[204:207], v211 offset:54272
	ds_read_b128 v[214:217], v211 offset:55296
	ds_read_b128 v[218:221], v211 offset:56320
	global_load_lds_dwordx4 v[222:223], off
	s_add_i32 m0, s66, 0x2000
	s_add_u32 s64, s64, 0x40080
	v_lshl_add_u64 v[222:223], v[224:225], 0, s[22:23]
	s_addc_u32 s65, s65, 0
	s_add_i32 s66, s83, s33
	global_load_lds_dwordx4 v[222:223], off
	v_lshl_add_u64 v[222:223], s[64:65], 0, v[180:181]
	s_mov_b32 m0, s66
	s_nop 0
	global_load_lds_dwordx4 v[222:223], off
	v_lshl_add_u64 v[222:223], s[64:65], 0, v[182:183]
	s_add_i32 m0, s66, 0x2000
	s_nop 0
	global_load_lds_dwordx4 v[222:223], off
	v_lshl_add_u64 v[222:223], v[226:227], 0, s[22:23]
	s_mov_b32 m0, s72
	s_nop 0
	global_load_lds_dwordx4 v[222:223], off
	v_lshl_add_u64 v[222:223], v[228:229], 0, s[22:23]
	s_mov_b32 m0, s73
	s_nop 0
	global_load_lds_dwordx4 v[222:223], off
	s_waitcnt vmcnt(8)
	s_waitcnt lgkmcnt(0)
	s_barrier
	s_waitcnt lgkmcnt(0)
	v_mfma_f32_16x16x32_bf16 v[94:97], v[58:61], v[162:165], v[94:97]
	v_mfma_f32_16x16x32_bf16 v[90:93], v[66:69], v[162:165], v[90:93]
	v_mfma_f32_16x16x32_bf16 v[46:49], v[58:61], v[170:173], v[46:49]
	v_mfma_f32_16x16x32_bf16 v[42:45], v[66:69], v[170:173], v[42:45]
	v_mfma_f32_16x16x32_bf16 v[30:33], v[58:61], v[200:203], v[30:33]
	v_mfma_f32_16x16x32_bf16 v[26:29], v[66:69], v[200:203], v[26:29]
	v_mfma_f32_16x16x32_bf16 v[14:17], v[58:61], v[214:217], v[14:17]
	v_mfma_f32_16x16x32_bf16 v[10:13], v[66:69], v[214:217], v[10:13]
	v_mfma_f32_16x16x32_bf16 v[94:97], v[62:65], v[166:169], v[94:97]
	v_mfma_f32_16x16x32_bf16 v[90:93], v[70:73], v[166:169], v[90:93]
	v_mfma_f32_16x16x32_bf16 v[46:49], v[62:65], v[174:177], v[46:49]
	v_mfma_f32_16x16x32_bf16 v[42:45], v[70:73], v[174:177], v[42:45]
	v_mfma_f32_16x16x32_bf16 v[30:33], v[62:65], v[204:207], v[30:33]
	v_mfma_f32_16x16x32_bf16 v[26:29], v[70:73], v[204:207], v[26:29]
	v_mfma_f32_16x16x32_bf16 v[14:17], v[62:65], v[218:221], v[14:17]
	v_mfma_f32_16x16x32_bf16 v[10:13], v[70:73], v[218:221], v[10:13]
	v_mfma_f32_16x16x32_bf16 v[54:57], v[74:77], v[162:165], v[54:57]
	v_mfma_f32_16x16x32_bf16 v[50:53], v[82:85], v[162:165], v[50:53]
	v_mfma_f32_16x16x32_bf16 v[38:41], v[74:77], v[170:173], v[38:41]
	v_mfma_f32_16x16x32_bf16 v[34:37], v[82:85], v[170:173], v[34:37]
	v_mfma_f32_16x16x32_bf16 v[22:25], v[74:77], v[200:203], v[22:25]
	v_mfma_f32_16x16x32_bf16 v[18:21], v[82:85], v[200:203], v[18:21]
	v_mfma_f32_16x16x32_bf16 v[6:9], v[74:77], v[214:217], v[6:9]
	v_mfma_f32_16x16x32_bf16 v[2:5], v[82:85], v[214:217], v[2:5]
	v_mfma_f32_16x16x32_bf16 v[54:57], v[78:81], v[166:169], v[54:57]
	v_mfma_f32_16x16x32_bf16 v[50:53], v[86:89], v[166:169], v[50:53]
	v_mfma_f32_16x16x32_bf16 v[38:41], v[78:81], v[174:177], v[38:41]
	v_mfma_f32_16x16x32_bf16 v[34:37], v[86:89], v[174:177], v[34:37]
	v_mfma_f32_16x16x32_bf16 v[22:25], v[78:81], v[204:207], v[22:25]
	v_mfma_f32_16x16x32_bf16 v[18:21], v[86:89], v[204:207], v[18:21]
	v_mfma_f32_16x16x32_bf16 v[6:9], v[78:81], v[218:221], v[6:9]
	v_mfma_f32_16x16x32_bf16 v[2:5], v[86:89], v[218:221], v[2:5]
	s_barrier
	s_add_i32 s81, s81, 2
	s_add_u32 s62, s62, 0x100
	s_addc_u32 s63, s63, 0
	s_add_u32 s79, s79, 0x100
	s_addc_u32 s80, s80, 0
	s_cmp_gt_u32 s81, 13
	s_cbranch_scc0 .LBB0_713
	s_and_b64 vcc, exec, s[24:25]
	s_cbranch_vccz .LBB0_716
	s_barrier

; #define PG8_STAGE(bufoff, gbase, voff) do { _Pragma("unroll") for (int _i = 0; _i < 2; ++_i) \
;         __builtin_amdgcn_global_load_lds((const unsigned*)((const char*)(gbase) + (voff)[_i]), (PG8_LAS unsigned*)(lds + (bufoff) + ldsw + _i * 8192), 16, 0, 0); } while (0)
; #define PG8_LDA(dst, b, h) do { _Pragma("unroll") for (int m = 0; m < 4; ++m) _Pragma("unroll") for (int k = 0; k < 2; ++k) dst[m][k] = *(const PG8_LAS bf16x8*)(lds + PG8_SA(b, h) + aoff + m * 2048 + k * 1024); } while (0)
; #define PG8_LDB(dst, b, h) do { _Pragma("unroll") for (int n = 0; n < 2; ++n) _Pragma("unroll") for (int k = 0; k < 2; ++k) dst[n][k] = *(const PG8_LAS bf16x8*)(lds + PG8_SB(b, h) + boff + n * 2048 + k * 1024); } while (0)
; #define PG8_WAIT_V(n) asm volatile("s_waitcnt vmcnt(" #n ")" ::: "memory")
; #define PG8_WAIT_L(n) asm volatile("s_waitcnt lgkmcnt(" #n ")" ::: "memory")
; #define PG8_BAR __builtin_amdgcn_s_barrier()
; #define PG8_SCHED __builtin_amdgcn_sched_barrier(0)
; template <class Epi, class Sched, bool ALIGN_EPI = false, bool SP2 = false>
; __device__ __forceinline__ void gemm_phase(PG8_LAS unsigned char* lds, const Gemm g, const Sched& S, const Epi& E) {
;     ...
;         const bool has_next = S.next(ui + 1, nxt);
;         const char* nA = has_next ? (const char*)g.A + (size_t)nxt.pm * tstep : cA; const char* nB = has_next ? (const char*)g.Bt + (size_t)nxt.pn * tstep : cB;
;         for (int t = 0; t < nt; t += 2) {
;             const bool last = (t == nt - 2);
;             const char* a1 = cA + (size_t)(t + 1) * kstep;
;             const char* a2 = last ? nA : cA + (size_t)(t + 2) * kstep; const char* b2 = last ? nB : cB + (size_t)(t + 2) * kstep;
;             const char* a3 = a2 + kstep; const char* b3 = b2 + kstep;
;             if (last && has_next) S.a_ready(nxt);
;             if constexpr (SP2) {
;             PG8_LDB(B0, 0, 0); PG8_LDB(B1, 0, 1); PG8_SCHED; PG8_LDA(At, 0, 0); PG8_STAGE(PG8_SA(1, 1), a1 + hstep, voffA);
;             PG8_WAIT_V(8); PG8_WAIT_L(0); PG8_BAR; PG8_MMA(0, 0, At, B0); PG8_MMA(0, 1, At, B1); PG8_BAR; PG8_SCHED;
;             PG8_LDA(At, 0, 1); PG8_STAGE(PG8_SB(0, 0), b2, voffB); PG8_STAGE(PG8_SB(0, 1), b2 + hstep, voffB); PG8_STAGE(PG8_SA(0, 0), a2, voffA);
;             PG8_WAIT_V(8); PG8_WAIT_L(0); PG8_BAR; PG8_MMA(1, 0, At, B0); PG8_MMA(1, 1, At, B1); PG8_BAR; PG8_SCHED;
.LBB0_804:
	s_add_u32 s40, s33, s36
	s_addc_u32 s41, s56, s37
	s_add_u32 s40, s40, 0x5000100
	s_addc_u32 s41, s41, 0
	s_add_u32 s64, s58, s36
	s_addc_u32 s65, s62, s37
	s_add_i32 s66, 0, 0x10000
	s_cmpk_eq_i32 s36, 0x700
	s_cselect_b32 s47, s17, s41
	s_cselect_b32 s46, s16, s40
	v_add_u32_e32 v111, s66, v101
	s_cselect_b32 s41, s1, s65
	s_cselect_b32 s40, s0, s64
	s_add_i32 s67, 0, 0x14000
	ds_read_b128 v[156:159], v111
	ds_read_b128 v[170:173], v111 offset:1024
	ds_read_b128 v[174:177], v111 offset:2048
	ds_read_b128 v[178:181], v111 offset:3072
	v_add_u32_e32 v111, s67, v101
	ds_read_b128 v[182:185], v111
	ds_read_b128 v[186:189], v111 offset:1024
	ds_read_b128 v[190:193], v111 offset:2048
	ds_read_b128 v[194:197], v111 offset:3072
	v_lshl_add_u64 v[112:113], v[106:107], 0, s[36:37]
	s_add_i32 m0, s74, 0xc000
	ds_read_b128 v[198:201], v110
	ds_read_b128 v[202:205], v110 offset:1024
	ds_read_b128 v[206:209], v110 offset:2048
	ds_read_b128 v[210:213], v110 offset:3072
	ds_read_b128 v[214:217], v110 offset:4096
	ds_read_b128 v[218:221], v110 offset:5120
	ds_read_b128 v[222:225], v110 offset:6144
	ds_read_b128 v[226:229], v110 offset:7168
	global_load_lds_dwordx4 v[112:113], off
	v_lshl_add_u64 v[112:113], v[108:109], 0, s[36:37]
	s_add_i32 m0, s74, 0xe000
	s_nop 0
	global_load_lds_dwordx4 v[112:113], off
	s_waitcnt vmcnt(8)
	s_waitcnt lgkmcnt(0)
	s_barrier
	s_waitcnt lgkmcnt(0)
	v_mfma_f32_16x16x32_bf16 v[142:145], v[156:159], v[198:201], v[142:145]
	v_mfma_f32_16x16x32_bf16 v[138:141], v[174:177], v[198:201], v[138:141]
	v_mfma_f32_16x16x32_bf16 v[126:129], v[156:159], v[206:209], v[126:129]
	v_mfma_f32_16x16x32_bf16 v[122:125], v[174:177], v[206:209], v[122:125]
	v_mfma_f32_16x16x32_bf16 v[94:97], v[156:159], v[214:217], v[94:97]
	v_mfma_f32_16x16x32_bf16 v[90:93], v[174:177], v[214:217], v[90:93]
	v_mfma_f32_16x16x32_bf16 v[78:81], v[156:159], v[222:225], v[78:81]
	v_mfma_f32_16x16x32_bf16 v[74:77], v[174:177], v[222:225], v[74:77]
	v_mfma_f32_16x16x32_bf16 v[142:145], v[170:173], v[202:205], v[142:145]
	v_mfma_f32_16x16x32_bf16 v[138:141], v[178:181], v[202:205], v[138:141]
	v_mfma_f32_16x16x32_bf16 v[126:129], v[170:173], v[210:213], v[126:129]
	v_mfma_f32_16x16x32_bf16 v[122:125], v[178:181], v[210:213], v[122:125]
	v_mfma_f32_16x16x32_bf16 v[94:97], v[170:173], v[218:221], v[94:97]
	v_mfma_f32_16x16x32_bf16 v[90:93], v[178:181], v[218:221], v[90:93]
	v_mfma_f32_16x16x32_bf16 v[78:81], v[170:173], v[226:229], v[78:81]
	v_mfma_f32_16x16x32_bf16 v[74:77], v[178:181], v[226:229], v[74:77]
	v_mfma_f32_16x16x32_bf16 v[134:137], v[182:185], v[198:201], v[134:137]
	v_mfma_f32_16x16x32_bf16 v[130:133], v[190:193], v[198:201], v[130:133]
	v_mfma_f32_16x16x32_bf16 v[118:121], v[182:185], v[206:209], v[118:121]
	v_mfma_f32_16x16x32_bf16 v[112:115], v[190:193], v[206:209], v[114:117]
	v_mfma_f32_16x16x32_bf16 v[86:89], v[182:185], v[214:217], v[86:89]
	v_mfma_f32_16x16x32_bf16 v[82:85], v[190:193], v[214:217], v[82:85]
	v_mfma_f32_16x16x32_bf16 v[70:73], v[182:185], v[222:225], v[70:73]
	v_mfma_f32_16x16x32_bf16 v[66:69], v[190:193], v[222:225], v[66:69]
	v_mfma_f32_16x16x32_bf16 v[134:137], v[186:189], v[202:205], v[134:137]
	v_mfma_f32_16x16x32_bf16 v[130:133], v[194:197], v[202:205], v[130:133]
	v_mfma_f32_16x16x32_bf16 v[118:121], v[186:189], v[210:213], v[118:121]
	v_mfma_f32_16x16x32_bf16 v[112:115], v[194:197], v[210:213], v[112:115]
	v_mfma_f32_16x16x32_bf16 v[86:89], v[186:189], v[218:221], v[86:89]
	v_mfma_f32_16x16x32_bf16 v[82:85], v[194:197], v[218:221], v[82:85]
	v_mfma_f32_16x16x32_bf16 v[70:73], v[186:189], v[226:229], v[70:73]
	v_mfma_f32_16x16x32_bf16 v[66:69], v[194:197], v[226:229], v[66:69]
	s_barrier
	s_add_i32 s64, s66, s73
	v_lshl_add_u64 v[230:231], s[40:41], 0, v[148:149]
	s_mov_b32 m0, s64
	ds_read_b128 v[198:201], v110 offset:16384
	ds_read_b128 v[202:205], v110 offset:17408
	ds_read_b128 v[206:209], v110 offset:18432
	ds_read_b128 v[210:213], v110 offset:19456
	ds_read_b128 v[214:217], v110 offset:20480
	ds_read_b128 v[218:221], v110 offset:21504
	ds_read_b128 v[222:225], v110 offset:22528
	ds_read_b128 v[226:229], v110 offset:23552
	global_load_lds_dwordx4 v[230:231], off
	s_add_i32 m0, s64, 0x2000
	s_add_u32 s64, s40, 0x40000
	v_lshl_add_u64 v[232:233], s[40:41], 0, v[104:105]
	s_addc_u32 s65, s41, 0
	s_add_i32 s66, s67, s73
	global_load_lds_dwordx4 v[232:233], off
	v_lshl_add_u64 v[116:117], s[64:65], 0, v[148:149]
	s_mov_b32 m0, s66
	v_lshl_add_u64 v[234:235], s[46:47], 0, v[98:99]
	global_load_lds_dwordx4 v[116:117], off
	v_lshl_add_u64 v[116:117], s[64:65], 0, v[104:105]
	s_add_i32 m0, s66, 0x2000
	v_lshl_add_u64 v[236:237], s[46:47], 0, v[102:103]
	global_load_lds_dwordx4 v[116:117], off
	s_mov_b32 m0, s74
	s_nop 0
	global_load_lds_dwordx4 v[234:235], off
	s_mov_b32 m0, s75
	s_nop 0
	global_load_lds_dwordx4 v[236:237], off
	s_waitcnt vmcnt(8)
	s_waitcnt lgkmcnt(0)
	s_barrier
; #define PG8_STAGE(bufoff, gbase, voff) do { _Pragma("unroll") for (int _i = 0; _i < 2; ++_i) \
;         __builtin_amdgcn_global_load_lds((const unsigned*)((const char*)(gbase) + (voff)[_i]), (PG8_LAS unsigned*)(lds + (bufoff) + ldsw + _i * 8192), 16, 0, 0); } while (0)
; #define PG8_LDA(dst, b, h) do { _Pragma("unroll") for (int m = 0; m < 4; ++m) _Pragma("unroll") for (int k = 0; k < 2; ++k) dst[m][k] = *(const PG8_LAS bf16x8*)(lds + PG8_SA(b, h) + aoff + m * 2048 + k * 1024); } while (0)
; #define PG8_LDB(dst, b, h) do { _Pragma("unroll") for (int n = 0; n < 2; ++n) _Pragma("unroll") for (int k = 0; k < 2; ++k) dst[n][k] = *(const PG8_LAS bf16x8*)(lds + PG8_SB(b, h) + boff + n * 2048 + k * 1024); } while (0)
; #define PG8_MMA(ai, bj, At, Bt) do { __builtin_amdgcn_s_setprio(1); _Pragma("unroll") for (int m = 0; m < 4; ++m) _Pragma("unroll") for (int n = 0; n < 2; ++n) _Pragma("unroll") for (int k = 0; k < 2; ++k) \
;         acc[ai][bj][m][n] = __builtin_amdgcn_mfma_f32_16x16x32_bf16(Bt[n][k], At[m][k], acc[ai][bj][m][n], 0, 0, 0); __builtin_amdgcn_s_setprio(0); } while (0)
; #define PG8_WAIT_V(n) asm volatile("s_waitcnt vmcnt(" #n ")" ::: "memory")
; #define PG8_WAIT_L(n) asm volatile("s_waitcnt lgkmcnt(" #n ")" ::: "memory")
; #define PG8_BAR __builtin_amdgcn_s_barrier()
; #define PG8_SCHED __builtin_amdgcn_sched_barrier(0)
; template <class Epi, class Sched, bool ALIGN_EPI = false, bool SP2 = false>
; __device__ __forceinline__ void gemm_phase(PG8_LAS unsigned char* lds, const Gemm g, const Sched& S, const Epi& E) {
;     ...
;             PG8_WAIT_V(8); PG8_WAIT_L(0); PG8_BAR; PG8_MMA(1, 0, At, B0); PG8_MMA(1, 1, At, B1); PG8_BAR; PG8_SCHED;
;             PG8_LDB(B0, 1, 0); PG8_LDB(B1, 1, 1); PG8_SCHED; PG8_LDA(At, 1, 0); PG8_STAGE(PG8_SA(0, 1), a2 + hstep, voffA);
;             PG8_WAIT_V(8); PG8_WAIT_L(0); PG8_BAR; PG8_MMA(0, 0, At, B0); PG8_MMA(0, 1, At, B1); PG8_BAR; PG8_SCHED;
	s_waitcnt lgkmcnt(0)
	v_mfma_f32_16x16x32_bf16 v[62:65], v[156:159], v[198:201], v[62:65]
	v_mfma_f32_16x16x32_bf16 v[58:61], v[174:177], v[198:201], v[58:61]
	v_mfma_f32_16x16x32_bf16 v[46:49], v[156:159], v[206:209], v[46:49]
	v_mfma_f32_16x16x32_bf16 v[42:45], v[174:177], v[206:209], v[42:45]
	v_mfma_f32_16x16x32_bf16 v[30:33], v[156:159], v[214:217], v[30:33]
	v_mfma_f32_16x16x32_bf16 v[26:29], v[174:177], v[214:217], v[26:29]
	v_mfma_f32_16x16x32_bf16 v[14:17], v[156:159], v[222:225], v[14:17]
	v_mfma_f32_16x16x32_bf16 v[10:13], v[174:177], v[222:225], v[10:13]
	v_mfma_f32_16x16x32_bf16 v[62:65], v[170:173], v[202:205], v[62:65]
	v_mfma_f32_16x16x32_bf16 v[58:61], v[178:181], v[202:205], v[58:61]
	v_mfma_f32_16x16x32_bf16 v[46:49], v[170:173], v[210:213], v[46:49]
	v_mfma_f32_16x16x32_bf16 v[42:45], v[178:181], v[210:213], v[42:45]
	v_mfma_f32_16x16x32_bf16 v[30:33], v[170:173], v[218:221], v[30:33]
	v_mfma_f32_16x16x32_bf16 v[26:29], v[178:181], v[218:221], v[26:29]
	v_mfma_f32_16x16x32_bf16 v[14:17], v[170:173], v[226:229], v[14:17]
	v_mfma_f32_16x16x32_bf16 v[10:13], v[178:181], v[226:229], v[10:13]
	v_mfma_f32_16x16x32_bf16 v[54:57], v[182:185], v[198:201], v[54:57]
	v_mfma_f32_16x16x32_bf16 v[50:53], v[190:193], v[198:201], v[50:53]
	v_mfma_f32_16x16x32_bf16 v[38:41], v[182:185], v[206:209], v[38:41]
	v_mfma_f32_16x16x32_bf16 v[34:37], v[190:193], v[206:209], v[34:37]
	v_mfma_f32_16x16x32_bf16 v[22:25], v[182:185], v[214:217], v[22:25]
	v_mfma_f32_16x16x32_bf16 v[18:21], v[190:193], v[214:217], v[18:21]
	v_mfma_f32_16x16x32_bf16 v[6:9], v[182:185], v[222:225], v[6:9]
	v_mfma_f32_16x16x32_bf16 v[2:5], v[190:193], v[222:225], v[2:5]
	v_mfma_f32_16x16x32_bf16 v[54:57], v[186:189], v[202:205], v[54:57]
	v_mfma_f32_16x16x32_bf16 v[50:53], v[194:197], v[202:205], v[50:53]
	v_mfma_f32_16x16x32_bf16 v[38:41], v[186:189], v[210:213], v[38:41]
	v_mfma_f32_16x16x32_bf16 v[34:37], v[194:197], v[210:213], v[34:37]
	v_mfma_f32_16x16x32_bf16 v[22:25], v[186:189], v[218:221], v[22:25]
	v_mfma_f32_16x16x32_bf16 v[18:21], v[194:197], v[218:221], v[18:21]
	v_mfma_f32_16x16x32_bf16 v[6:9], v[186:189], v[226:229], v[6:9]
	v_mfma_f32_16x16x32_bf16 v[2:5], v[194:197], v[226:229], v[2:5]
	s_barrier
	s_add_i32 s64, 0, 0x18000
	v_add_u32_e32 v111, s64, v101
	s_add_i32 s65, 0, 0x1c000
	ds_read_b128 v[156:159], v111
	ds_read_b128 v[170:173], v111 offset:1024
	ds_read_b128 v[174:177], v111 offset:2048
	ds_read_b128 v[178:181], v111 offset:3072
	v_add_u32_e32 v111, s65, v101
	ds_read_b128 v[182:185], v111
	ds_read_b128 v[186:189], v111 offset:1024
	ds_read_b128 v[190:193], v111 offset:2048
	ds_read_b128 v[194:197], v111 offset:3072
	s_add_u32 s46, s46, 0x40000
	s_addc_u32 s47, s47, 0
	s_mov_b32 m0, vcc_hi
	v_lshl_add_u64 v[116:117], s[46:47], 0, v[98:99]
	ds_read_b128 v[198:201], v110 offset:32768
	ds_read_b128 v[202:205], v110 offset:33792
	ds_read_b128 v[206:209], v110 offset:34816
	ds_read_b128 v[210:213], v110 offset:35840
	ds_read_b128 v[214:217], v110 offset:36864
	ds_read_b128 v[218:221], v110 offset:37888
	ds_read_b128 v[222:225], v110 offset:38912
	ds_read_b128 v[226:229], v110 offset:39936
	global_load_lds_dwordx4 v[116:117], off
	v_lshl_add_u64 v[116:117], s[46:47], 0, v[102:103]
	s_mov_b32 m0, s3
	s_nop 0
	global_load_lds_dwordx4 v[116:117], off
	s_waitcnt vmcnt(8)
	s_waitcnt lgkmcnt(0)
	s_barrier
	s_waitcnt lgkmcnt(0)
	v_mfma_f32_16x16x32_bf16 v[142:145], v[156:159], v[198:201], v[142:145]
	v_mfma_f32_16x16x32_bf16 v[138:141], v[174:177], v[198:201], v[138:141]
	v_mfma_f32_16x16x32_bf16 v[126:129], v[156:159], v[206:209], v[126:129]
	v_mfma_f32_16x16x32_bf16 v[122:125], v[174:177], v[206:209], v[122:125]
	v_mfma_f32_16x16x32_bf16 v[94:97], v[156:159], v[214:217], v[94:97]
	v_mfma_f32_16x16x32_bf16 v[90:93], v[174:177], v[214:217], v[90:93]
	v_mfma_f32_16x16x32_bf16 v[78:81], v[156:159], v[222:225], v[78:81]
	v_mfma_f32_16x16x32_bf16 v[74:77], v[174:177], v[222:225], v[74:77]
	v_mfma_f32_16x16x32_bf16 v[142:145], v[170:173], v[202:205], v[142:145]
	v_mfma_f32_16x16x32_bf16 v[138:141], v[178:181], v[202:205], v[138:141]
	v_mfma_f32_16x16x32_bf16 v[126:129], v[170:173], v[210:213], v[126:129]
	v_mfma_f32_16x16x32_bf16 v[122:125], v[178:181], v[210:213], v[122:125]
	v_mfma_f32_16x16x32_bf16 v[94:97], v[170:173], v[218:221], v[94:97]
	v_mfma_f32_16x16x32_bf16 v[90:93], v[178:181], v[218:221], v[90:93]
	v_mfma_f32_16x16x32_bf16 v[78:81], v[170:173], v[226:229], v[78:81]
	v_mfma_f32_16x16x32_bf16 v[74:77], v[178:181], v[226:229], v[74:77]
	v_mfma_f32_16x16x32_bf16 v[134:137], v[182:185], v[198:201], v[134:137]
	v_mfma_f32_16x16x32_bf16 v[130:133], v[190:193], v[198:201], v[130:133]
	v_mfma_f32_16x16x32_bf16 v[116:119], v[182:185], v[206:209], v[118:121]
	v_mfma_f32_16x16x32_bf16 v[112:115], v[190:193], v[206:209], v[112:115]
	v_mfma_f32_16x16x32_bf16 v[86:89], v[182:185], v[214:217], v[86:89]
	v_mfma_f32_16x16x32_bf16 v[82:85], v[190:193], v[214:217], v[82:85]
	v_mfma_f32_16x16x32_bf16 v[70:73], v[182:185], v[222:225], v[70:73]
	v_mfma_f32_16x16x32_bf16 v[66:69], v[190:193], v[222:225], v[66:69]
	v_mfma_f32_16x16x32_bf16 v[134:137], v[186:189], v[202:205], v[134:137]
	v_mfma_f32_16x16x32_bf16 v[130:133], v[194:197], v[202:205], v[130:133]
	v_mfma_f32_16x16x32_bf16 v[118:121], v[186:189], v[210:213], v[116:119]
	v_mfma_f32_16x16x32_bf16 v[114:117], v[194:197], v[210:213], v[112:115]
	v_mfma_f32_16x16x32_bf16 v[86:89], v[186:189], v[218:221], v[86:89]
	v_mfma_f32_16x16x32_bf16 v[82:85], v[194:197], v[218:221], v[82:85]
	v_mfma_f32_16x16x32_bf16 v[70:73], v[186:189], v[226:229], v[70:73]
	v_mfma_f32_16x16x32_bf16 v[66:69], v[194:197], v[226:229], v[66:69]
	s_barrier
; #define PG8_STAGE(bufoff, gbase, voff) do { _Pragma("unroll") for (int _i = 0; _i < 2; ++_i) \
;         __builtin_amdgcn_global_load_lds((const unsigned*)((const char*)(gbase) + (voff)[_i]), (PG8_LAS unsigned*)(lds + (bufoff) + ldsw + _i * 8192), 16, 0, 0); } while (0)
; #define PG8_LDA(dst, b, h) do { _Pragma("unroll") for (int m = 0; m < 4; ++m) _Pragma("unroll") for (int k = 0; k < 2; ++k) dst[m][k] = *(const PG8_LAS bf16x8*)(lds + PG8_SA(b, h) + aoff + m * 2048 + k * 1024); } while (0)
; #define PG8_MMA(ai, bj, At, Bt) do { __builtin_amdgcn_s_setprio(1); _Pragma("unroll") for (int m = 0; m < 4; ++m) _Pragma("unroll") for (int n = 0; n < 2; ++n) _Pragma("unroll") for (int k = 0; k < 2; ++k) \
;         acc[ai][bj][m][n] = __builtin_amdgcn_mfma_f32_16x16x32_bf16(Bt[n][k], At[m][k], acc[ai][bj][m][n], 0, 0, 0); __builtin_amdgcn_s_setprio(0); } while (0)
; #define PG8_WAIT_V(n) asm volatile("s_waitcnt vmcnt(" #n ")" ::: "memory")
; #define PG8_WAIT_L(n) asm volatile("s_waitcnt lgkmcnt(" #n ")" ::: "memory")
; #define PG8_BAR __builtin_amdgcn_s_barrier()
; #define PG8_SCHED __builtin_amdgcn_sched_barrier(0)
; template <class Epi, class Sched, bool ALIGN_EPI = false, bool SP2 = false>
; __device__ __forceinline__ void gemm_phase(PG8_LAS unsigned char* lds, const Gemm g, const Sched& S, const Epi& E) {
;     ...
;             PG8_LDA(At, 1, 1); PG8_STAGE(PG8_SB(1, 0), b3, voffB); PG8_STAGE(PG8_SB(1, 1), b3 + hstep, voffB); PG8_STAGE(PG8_SA(1, 0), a3, voffA);
;             PG8_WAIT_V(8); PG8_WAIT_L(0); PG8_BAR; PG8_MMA(1, 0, At, B0); PG8_MMA(1, 1, At, B1); PG8_BAR; PG8_SCHED;
;     ...
;     PG8_WAIT_V(0);
;     if constexpr (!ALIGN_EPI) { if (wr == 0) PG8_BAR; }
;     PG8_BAR;
	s_add_i32 s46, s64, s73
	v_lshl_add_u64 v[112:113], v[230:231], 0, s[12:13]
	s_mov_b32 m0, s46
	ds_read_b128 v[198:201], v110 offset:49152
	ds_read_b128 v[202:205], v110 offset:50176
	ds_read_b128 v[206:209], v110 offset:51200
	ds_read_b128 v[210:213], v110 offset:52224
	ds_read_b128 v[214:217], v110 offset:53248
	ds_read_b128 v[218:221], v110 offset:54272
	ds_read_b128 v[222:225], v110 offset:55296
	ds_read_b128 v[226:229], v110 offset:56320
	global_load_lds_dwordx4 v[112:113], off
	s_add_i32 m0, s46, 0x2000
	s_add_u32 s40, s40, 0x40080
	v_lshl_add_u64 v[112:113], v[232:233], 0, s[12:13]
	s_addc_u32 s41, s41, 0
	s_add_i32 s46, s65, s73
	global_load_lds_dwordx4 v[112:113], off
	v_lshl_add_u64 v[112:113], s[40:41], 0, v[148:149]
	s_mov_b32 m0, s46
	s_nop 0
	global_load_lds_dwordx4 v[112:113], off
	v_lshl_add_u64 v[112:113], s[40:41], 0, v[104:105]
	s_add_i32 m0, s46, 0x2000
	s_nop 0
	global_load_lds_dwordx4 v[112:113], off
	v_lshl_add_u64 v[112:113], v[234:235], 0, s[12:13]
	s_mov_b32 m0, s15
	s_nop 0
	global_load_lds_dwordx4 v[112:113], off
	v_lshl_add_u64 v[112:113], v[236:237], 0, s[12:13]
	s_mov_b32 m0, s19
	s_nop 0
	global_load_lds_dwordx4 v[112:113], off
	s_waitcnt vmcnt(8)
	s_waitcnt lgkmcnt(0)
	s_barrier
	s_waitcnt lgkmcnt(0)
	v_mfma_f32_16x16x32_bf16 v[62:65], v[156:159], v[198:201], v[62:65]
	v_mfma_f32_16x16x32_bf16 v[58:61], v[174:177], v[198:201], v[58:61]
	v_mfma_f32_16x16x32_bf16 v[46:49], v[156:159], v[206:209], v[46:49]
	v_mfma_f32_16x16x32_bf16 v[42:45], v[174:177], v[206:209], v[42:45]
	v_mfma_f32_16x16x32_bf16 v[30:33], v[156:159], v[214:217], v[30:33]
	v_mfma_f32_16x16x32_bf16 v[26:29], v[174:177], v[214:217], v[26:29]
	v_mfma_f32_16x16x32_bf16 v[14:17], v[156:159], v[222:225], v[14:17]
	v_mfma_f32_16x16x32_bf16 v[10:13], v[174:177], v[222:225], v[10:13]
	v_mfma_f32_16x16x32_bf16 v[62:65], v[170:173], v[202:205], v[62:65]
	v_mfma_f32_16x16x32_bf16 v[58:61], v[178:181], v[202:205], v[58:61]
	v_mfma_f32_16x16x32_bf16 v[46:49], v[170:173], v[210:213], v[46:49]
	v_mfma_f32_16x16x32_bf16 v[42:45], v[178:181], v[210:213], v[42:45]
	v_mfma_f32_16x16x32_bf16 v[30:33], v[170:173], v[218:221], v[30:33]
	v_mfma_f32_16x16x32_bf16 v[26:29], v[178:181], v[218:221], v[26:29]
	v_mfma_f32_16x16x32_bf16 v[14:17], v[170:173], v[226:229], v[14:17]
	v_mfma_f32_16x16x32_bf16 v[10:13], v[178:181], v[226:229], v[10:13]
	v_mfma_f32_16x16x32_bf16 v[54:57], v[182:185], v[198:201], v[54:57]
	v_mfma_f32_16x16x32_bf16 v[50:53], v[190:193], v[198:201], v[50:53]
	v_mfma_f32_16x16x32_bf16 v[38:41], v[182:185], v[206:209], v[38:41]
	v_mfma_f32_16x16x32_bf16 v[34:37], v[190:193], v[206:209], v[34:37]
	v_mfma_f32_16x16x32_bf16 v[22:25], v[182:185], v[214:217], v[22:25]
	v_mfma_f32_16x16x32_bf16 v[18:21], v[190:193], v[214:217], v[18:21]
	v_mfma_f32_16x16x32_bf16 v[6:9], v[182:185], v[222:225], v[6:9]
	v_mfma_f32_16x16x32_bf16 v[2:5], v[190:193], v[222:225], v[2:5]
	v_mfma_f32_16x16x32_bf16 v[54:57], v[186:189], v[202:205], v[54:57]
	v_mfma_f32_16x16x32_bf16 v[50:53], v[194:197], v[202:205], v[50:53]
	v_mfma_f32_16x16x32_bf16 v[38:41], v[186:189], v[210:213], v[38:41]
	v_mfma_f32_16x16x32_bf16 v[34:37], v[194:197], v[210:213], v[34:37]
	v_mfma_f32_16x16x32_bf16 v[22:25], v[186:189], v[218:221], v[22:25]
	v_mfma_f32_16x16x32_bf16 v[18:21], v[194:197], v[218:221], v[18:21]
	v_mfma_f32_16x16x32_bf16 v[6:9], v[186:189], v[226:229], v[6:9]
	v_mfma_f32_16x16x32_bf16 v[2:5], v[194:197], v[226:229], v[2:5]
	s_barrier
	s_add_i32 s63, s63, 2
	s_add_u32 s36, s36, 0x100
	s_addc_u32 s37, s37, 0
	s_cmp_lt_u32 s63, 14
	s_cbranch_scc1 .LBB0_804
	s_waitcnt vmcnt(0)
	s_cmpk_gt_u32 s43, 0xff
	s_cbranch_scc1 .LBB0_807
	s_barrier
